# v40 + residual epilogue (x += acc) of the output and down projections: next quarter's loads issued before this quarter's stores (second register set), counted waits that never wait for a store
# speedup vs baseline: 1.0056x; 1.0056x over previous
;     DI void operator()(const f32x4 (&acc)[2][2][4][2], const Unit& u, int wr, int wc, int fr, int fq) const {
;         const int rowb = u.pm * 256 + wr * 64 + fr, colb = u.pn * 256 + wc * 32 + 8 * fq;
; #pragma unroll
;         for (int aq = 0; aq < 4; ++aq) {
;             const int ai = aq >> 1, m0 = (aq & 1) * 2;
;             f32x4 pre[4][2][2];
; #pragma unroll
;             for (int m = m0; m < m0 + 2; ++m)
; #pragma unroll
;                 for (int bj = 0; bj < 2; ++bj) { const f32x4* p = (const f32x4*)(x + (size_t)(rowb + ai * 128 + m * 16) * 1024 + colb + bj * 128); pre[m][bj][0] = p[0]; pre[m][bj][1] = p[1]; }
; #pragma unroll
;             for (int m = m0; m < m0 + 2; ++m)
; #pragma unroll
;                 for (int bj = 0; bj < 2; ++bj) { f32x4* p = (f32x4*)(x + (size_t)(rowb + ai * 128 + m * 16) * 1024 + colb + bj * 128); p[0] = pre[m][bj][0] + acc[ai][bj][m][0]; p[1] = pre[m][bj][1] + acc[ai][bj][m][1]; }
;         }
;     }
.LBB0_150:
	v_lshl_or_b32 v140, s56, 8, v150
	v_lshl_add_u32 v146, s55, 8, v148
	v_ashrrev_i32_e32 v141, 31, v140
	v_lshlrev_b64 v[140:141], 2, v[140:141]
	v_ashrrev_i32_e32 v147, 31, v146
	v_lshl_add_u64 v[142:143], s[16:17], 0, v[140:141]
	v_lshlrev_b64 v[144:145], 12, v[146:147]
	v_lshl_add_u64 v[184:185], v[142:143], 0, v[144:145]
	v_mov_b32_e32 v186, v184
	v_mov_b32_e32 v187, v185
	s_mov_b64 s[20:21], 0x10000
	v_lshl_add_u64 v[146:147], v[184:185], 0, s[20:21]
	global_load_dwordx4 v[152:155], v[186:187], off offset:16
	global_load_dwordx4 v[156:159], v[186:187], off
	global_load_dwordx4 v[160:163], v[186:187], off offset:528
	global_load_dwordx4 v[164:167], v[186:187], off offset:512
	global_load_dwordx4 v[168:171], v[146:147], off offset:16
	global_load_dwordx4 v[172:175], v[146:147], off
	global_load_dwordx4 v[176:179], v[146:147], off offset:528
	global_load_dwordx4 v[180:183], v[146:147], off offset:512
	s_mov_b64 s[20:21], 0x20000
	v_lshl_add_u64 v[140:141], v[184:185], 0, s[20:21]
	s_mov_b64 s[20:21], 0x30000
	v_lshl_add_u64 v[144:145], v[184:185], 0, s[20:21]
	global_load_dwordx4 v[188:191], v[140:141], off offset:16
	global_load_dwordx4 v[192:195], v[140:141], off
	global_load_dwordx4 v[204:207], v[140:141], off offset:528
	global_load_dwordx4 v[208:211], v[140:141], off offset:512
	global_load_dwordx4 v[212:215], v[144:145], off offset:16
	global_load_dwordx4 v[216:219], v[144:145], off
	global_load_dwordx4 v[220:223], v[144:145], off offset:528
	global_load_dwordx4 v[224:227], v[144:145], off offset:512
	s_waitcnt vmcnt(8)
	v_pk_add_f32 v[122:123], v[122:123], v[152:153]
	v_pk_add_f32 v[124:125], v[124:125], v[154:155]
	global_store_dwordx4 v[186:187], v[122:125], off offset:16
	v_pk_add_f32 v[126:127], v[126:127], v[156:157]
	v_pk_add_f32 v[128:129], v[128:129], v[158:159]
	global_store_dwordx4 v[186:187], v[126:129], off
	v_pk_add_f32 v[106:107], v[106:107], v[160:161]
	v_pk_add_f32 v[108:109], v[108:109], v[162:163]
	global_store_dwordx4 v[186:187], v[106:109], off offset:528
	v_pk_add_f32 v[110:111], v[110:111], v[164:165]
	v_pk_add_f32 v[112:113], v[112:113], v[166:167]
	global_store_dwordx4 v[186:187], v[110:113], off offset:512
	v_pk_add_f32 v[114:115], v[114:115], v[168:169]
	v_pk_add_f32 v[116:117], v[116:117], v[170:171]
	global_store_dwordx4 v[146:147], v[114:117], off offset:16
	v_pk_add_f32 v[118:119], v[118:119], v[172:173]
	v_pk_add_f32 v[120:121], v[120:121], v[174:175]
	global_store_dwordx4 v[146:147], v[118:121], off
	v_pk_add_f32 v[98:99], v[98:99], v[176:177]
	v_pk_add_f32 v[100:101], v[100:101], v[178:179]
	global_store_dwordx4 v[146:147], v[98:101], off offset:528
	v_pk_add_f32 v[102:103], v[102:103], v[180:181]
	v_pk_add_f32 v[104:105], v[104:105], v[182:183]
	global_store_dwordx4 v[146:147], v[102:105], off offset:512
	s_mov_b64 s[20:21], 0x80000
	v_lshl_add_u64 v[186:187], v[184:185], 0, s[20:21]
	s_mov_b64 s[20:21], 0x90000
	v_lshl_add_u64 v[146:147], v[184:185], 0, s[20:21]
	global_load_dwordx4 v[152:155], v[186:187], off offset:16
	global_load_dwordx4 v[156:159], v[186:187], off
	global_load_dwordx4 v[160:163], v[186:187], off offset:528
	global_load_dwordx4 v[164:167], v[186:187], off offset:512
	global_load_dwordx4 v[168:171], v[146:147], off offset:16
	global_load_dwordx4 v[172:175], v[146:147], off
	global_load_dwordx4 v[176:179], v[146:147], off offset:528
	global_load_dwordx4 v[180:183], v[146:147], off offset:512
	s_waitcnt vmcnt(16)
;     DI void operator()(const f32x4 (&acc)[2][2][4][2], const Unit& u, int wr, int wc, int fr, int fq) const {
;         const int rowb = u.pm * 256 + wr * 64 + fr, colb = u.pn * 256 + wc * 32 + 8 * fq;
; #pragma unroll
;         for (int aq = 0; aq < 4; ++aq) {
;             const int ai = aq >> 1, m0 = (aq & 1) * 2;
;             f32x4 pre[4][2][2];
; #pragma unroll
;             for (int m = m0; m < m0 + 2; ++m)
; #pragma unroll
;                 for (int bj = 0; bj < 2; ++bj) { const f32x4* p = (const f32x4*)(x + (size_t)(rowb + ai * 128 + m * 16) * 1024 + colb + bj * 128); pre[m][bj][0] = p[0]; pre[m][bj][1] = p[1]; }
; #pragma unroll
;             for (int m = m0; m < m0 + 2; ++m)
; #pragma unroll
;                 for (int bj = 0; bj < 2; ++bj) { f32x4* p = (f32x4*)(x + (size_t)(rowb + ai * 128 + m * 16) * 1024 + colb + bj * 128); p[0] = pre[m][bj][0] + acc[ai][bj][m][0]; p[1] = pre[m][bj][1] + acc[ai][bj][m][1]; }
;         }
;     }
	v_pk_add_f32 v[90:91], v[90:91], v[188:189]
	v_pk_add_f32 v[92:93], v[92:93], v[190:191]
	global_store_dwordx4 v[140:141], v[90:93], off offset:16
	v_pk_add_f32 v[94:95], v[94:95], v[192:193]
	v_pk_add_f32 v[96:97], v[96:97], v[194:195]
	global_store_dwordx4 v[140:141], v[94:97], off
	v_pk_add_f32 v[74:75], v[74:75], v[204:205]
	v_pk_add_f32 v[76:77], v[76:77], v[206:207]
	global_store_dwordx4 v[140:141], v[74:77], off offset:528
	v_pk_add_f32 v[78:79], v[78:79], v[208:209]
	v_pk_add_f32 v[80:81], v[80:81], v[210:211]
	global_store_dwordx4 v[140:141], v[78:81], off offset:512
	v_pk_add_f32 v[82:83], v[82:83], v[212:213]
	v_pk_add_f32 v[84:85], v[84:85], v[214:215]
	global_store_dwordx4 v[144:145], v[82:85], off offset:16
	v_pk_add_f32 v[86:87], v[86:87], v[216:217]
	v_pk_add_f32 v[88:89], v[88:89], v[218:219]
	global_store_dwordx4 v[144:145], v[86:89], off
	v_pk_add_f32 v[66:67], v[66:67], v[220:221]
	v_pk_add_f32 v[68:69], v[68:69], v[222:223]
	global_store_dwordx4 v[144:145], v[66:69], off offset:528
	v_pk_add_f32 v[70:71], v[70:71], v[224:225]
	v_pk_add_f32 v[72:73], v[72:73], v[226:227]
	global_store_dwordx4 v[144:145], v[70:73], off offset:512
	s_mov_b64 s[20:21], 0xa0000
	v_lshl_add_u64 v[140:141], v[184:185], 0, s[20:21]
	s_mov_b64 s[20:21], 0xb0000
	v_lshl_add_u64 v[144:145], v[184:185], 0, s[20:21]
	global_load_dwordx4 v[188:191], v[140:141], off offset:16
	global_load_dwordx4 v[192:195], v[140:141], off
	global_load_dwordx4 v[204:207], v[140:141], off offset:528
	global_load_dwordx4 v[208:211], v[140:141], off offset:512
	global_load_dwordx4 v[212:215], v[144:145], off offset:16
	global_load_dwordx4 v[216:219], v[144:145], off
	global_load_dwordx4 v[220:223], v[144:145], off offset:528
	global_load_dwordx4 v[224:227], v[144:145], off offset:512
	s_waitcnt vmcnt(16)
	v_pk_add_f32 v[58:59], v[58:59], v[152:153]
	v_pk_add_f32 v[60:61], v[60:61], v[154:155]
	global_store_dwordx4 v[186:187], v[58:61], off offset:16
	v_pk_add_f32 v[62:63], v[62:63], v[156:157]
	v_pk_add_f32 v[64:65], v[64:65], v[158:159]
	global_store_dwordx4 v[186:187], v[62:65], off
	v_pk_add_f32 v[42:43], v[42:43], v[160:161]
	v_pk_add_f32 v[44:45], v[44:45], v[162:163]
	global_store_dwordx4 v[186:187], v[42:45], off offset:528
	v_pk_add_f32 v[46:47], v[46:47], v[164:165]
	v_pk_add_f32 v[48:49], v[48:49], v[166:167]
	global_store_dwordx4 v[186:187], v[46:49], off offset:512
	v_pk_add_f32 v[50:51], v[50:51], v[168:169]
	v_pk_add_f32 v[52:53], v[52:53], v[170:171]
	global_store_dwordx4 v[146:147], v[50:53], off offset:16
	v_pk_add_f32 v[54:55], v[54:55], v[172:173]
	v_pk_add_f32 v[56:57], v[56:57], v[174:175]
	global_store_dwordx4 v[146:147], v[54:57], off
	v_pk_add_f32 v[34:35], v[34:35], v[176:177]
	v_pk_add_f32 v[36:37], v[36:37], v[178:179]
	global_store_dwordx4 v[146:147], v[34:37], off offset:528
	v_pk_add_f32 v[38:39], v[38:39], v[180:181]
	v_pk_add_f32 v[40:41], v[40:41], v[182:183]
	global_store_dwordx4 v[146:147], v[38:41], off offset:512
	s_waitcnt vmcnt(8)
	v_pk_add_f32 v[24:25], v[24:25], v[188:189]
	v_pk_add_f32 v[26:27], v[26:27], v[190:191]
	global_store_dwordx4 v[140:141], v[24:27], off offset:16
	v_pk_add_f32 v[28:29], v[28:29], v[192:193]
	v_pk_add_f32 v[30:31], v[30:31], v[194:195]
	global_store_dwordx4 v[140:141], v[28:31], off
	v_pk_add_f32 v[8:9], v[8:9], v[204:205]
	v_pk_add_f32 v[10:11], v[10:11], v[206:207]
	global_store_dwordx4 v[140:141], v[8:11], off offset:528
	v_pk_add_f32 v[16:17], v[16:17], v[208:209]
	v_pk_add_f32 v[18:19], v[18:19], v[210:211]
	global_store_dwordx4 v[140:141], v[16:19], off offset:512
	v_pk_add_f32 v[12:13], v[12:13], v[212:213]
	v_pk_add_f32 v[14:15], v[14:15], v[214:215]
	global_store_dwordx4 v[144:145], v[12:15], off offset:16
	v_pk_add_f32 v[20:21], v[20:21], v[216:217]
	v_pk_add_f32 v[22:23], v[22:23], v[218:219]
	global_store_dwordx4 v[144:145], v[20:23], off
	v_pk_add_f32 v[0:1], v[0:1], v[220:221]
	v_pk_add_f32 v[2:3], v[2:3], v[222:223]
	global_store_dwordx4 v[144:145], v[0:3], off offset:528
	v_pk_add_f32 v[4:5], v[4:5], v[224:225]
	v_pk_add_f32 v[6:7], v[6:7], v[226:227]
	global_store_dwordx4 v[144:145], v[4:7], off offset:512
	s_mov_b64 s[20:21], -1
	s_and_b64 vcc, exec, s[4:5]
	s_cbranch_vccnz .LBB0_135
	s_andn2_b64 vcc, exec, s[38:39]
	s_cbranch_vccnz .LBB0_134
	s_barrier
	s_branch .LBB0_134

;     DI void operator()(const f32x4 (&acc)[2][2][4][2], const Unit& u, int wr, int wc, int fr, int fq) const {
;         const int rowb = u.pm * 256 + wr * 64 + fr, colb = u.pn * 256 + wc * 32 + 8 * fq;
; #pragma unroll
;         for (int aq = 0; aq < 4; ++aq) {
;             const int ai = aq >> 1, m0 = (aq & 1) * 2;
;             f32x4 pre[4][2][2];
; #pragma unroll
;             for (int m = m0; m < m0 + 2; ++m)
; #pragma unroll
;                 for (int bj = 0; bj < 2; ++bj) { const f32x4* p = (const f32x4*)(x + (size_t)(rowb + ai * 128 + m * 16) * 1024 + colb + bj * 128); pre[m][bj][0] = p[0]; pre[m][bj][1] = p[1]; }
; #pragma unroll
;             for (int m = m0; m < m0 + 2; ++m)
; #pragma unroll
;                 for (int bj = 0; bj < 2; ++bj) { f32x4* p = (f32x4*)(x + (size_t)(rowb + ai * 128 + m * 16) * 1024 + colb + bj * 128); p[0] = pre[m][bj][0] + acc[ai][bj][m][0]; p[1] = pre[m][bj][1] + acc[ai][bj][m][1]; }
;         }
;     }
.LBB0_223:
	v_lshl_or_b32 v140, s65, 8, v150
	v_lshl_add_u32 v146, s50, 8, v148
	v_ashrrev_i32_e32 v141, 31, v140
	v_lshlrev_b64 v[140:141], 2, v[140:141]
	v_ashrrev_i32_e32 v147, 31, v146
	v_lshl_add_u64 v[142:143], s[38:39], 0, v[140:141]
	v_lshlrev_b64 v[144:145], 12, v[146:147]
	v_lshl_add_u64 v[184:185], v[142:143], 0, v[144:145]
	v_mov_b32_e32 v186, v184
	v_mov_b32_e32 v187, v185
	s_mov_b64 s[20:21], 0x10000
	v_lshl_add_u64 v[146:147], v[184:185], 0, s[20:21]
	global_load_dwordx4 v[152:155], v[186:187], off offset:16
	global_load_dwordx4 v[156:159], v[186:187], off
	global_load_dwordx4 v[160:163], v[186:187], off offset:528
	global_load_dwordx4 v[164:167], v[186:187], off offset:512
	global_load_dwordx4 v[168:171], v[146:147], off offset:16
	global_load_dwordx4 v[172:175], v[146:147], off
	global_load_dwordx4 v[176:179], v[146:147], off offset:528
	global_load_dwordx4 v[180:183], v[146:147], off offset:512
	s_mov_b64 s[20:21], 0x20000
	v_lshl_add_u64 v[140:141], v[184:185], 0, s[20:21]
	s_mov_b64 s[20:21], 0x30000
	v_lshl_add_u64 v[144:145], v[184:185], 0, s[20:21]
	global_load_dwordx4 v[188:191], v[140:141], off offset:16
	global_load_dwordx4 v[192:195], v[140:141], off
	global_load_dwordx4 v[204:207], v[140:141], off offset:528
	global_load_dwordx4 v[208:211], v[140:141], off offset:512
	global_load_dwordx4 v[212:215], v[144:145], off offset:16
	global_load_dwordx4 v[216:219], v[144:145], off
	global_load_dwordx4 v[220:223], v[144:145], off offset:528
	global_load_dwordx4 v[224:227], v[144:145], off offset:512
	s_waitcnt vmcnt(8)
	v_pk_add_f32 v[122:123], v[122:123], v[152:153]
	v_pk_add_f32 v[124:125], v[124:125], v[154:155]
	global_store_dwordx4 v[186:187], v[122:125], off offset:16
	v_pk_add_f32 v[126:127], v[126:127], v[156:157]
	v_pk_add_f32 v[128:129], v[128:129], v[158:159]
	global_store_dwordx4 v[186:187], v[126:129], off
	v_pk_add_f32 v[106:107], v[106:107], v[160:161]
	v_pk_add_f32 v[108:109], v[108:109], v[162:163]
	global_store_dwordx4 v[186:187], v[106:109], off offset:528
	v_pk_add_f32 v[110:111], v[110:111], v[164:165]
	v_pk_add_f32 v[112:113], v[112:113], v[166:167]
	global_store_dwordx4 v[186:187], v[110:113], off offset:512
	v_pk_add_f32 v[114:115], v[114:115], v[168:169]
	v_pk_add_f32 v[116:117], v[116:117], v[170:171]
	global_store_dwordx4 v[146:147], v[114:117], off offset:16
	v_pk_add_f32 v[118:119], v[118:119], v[172:173]
	v_pk_add_f32 v[120:121], v[120:121], v[174:175]
	global_store_dwordx4 v[146:147], v[118:121], off
	v_pk_add_f32 v[98:99], v[98:99], v[176:177]
	v_pk_add_f32 v[100:101], v[100:101], v[178:179]
	global_store_dwordx4 v[146:147], v[98:101], off offset:528
	v_pk_add_f32 v[102:103], v[102:103], v[180:181]
	v_pk_add_f32 v[104:105], v[104:105], v[182:183]
	global_store_dwordx4 v[146:147], v[102:105], off offset:512
	s_mov_b64 s[20:21], 0x80000
	v_lshl_add_u64 v[186:187], v[184:185], 0, s[20:21]
	s_mov_b64 s[20:21], 0x90000
	v_lshl_add_u64 v[146:147], v[184:185], 0, s[20:21]
	global_load_dwordx4 v[152:155], v[186:187], off offset:16
	global_load_dwordx4 v[156:159], v[186:187], off
	global_load_dwordx4 v[160:163], v[186:187], off offset:528
	global_load_dwordx4 v[164:167], v[186:187], off offset:512
	global_load_dwordx4 v[168:171], v[146:147], off offset:16
	global_load_dwordx4 v[172:175], v[146:147], off
	global_load_dwordx4 v[176:179], v[146:147], off offset:528
	global_load_dwordx4 v[180:183], v[146:147], off offset:512
	s_waitcnt vmcnt(16)
;     DI void operator()(const f32x4 (&acc)[2][2][4][2], const Unit& u, int wr, int wc, int fr, int fq) const {
;         const int rowb = u.pm * 256 + wr * 64 + fr, colb = u.pn * 256 + wc * 32 + 8 * fq;
; #pragma unroll
;         for (int aq = 0; aq < 4; ++aq) {
;             const int ai = aq >> 1, m0 = (aq & 1) * 2;
;             f32x4 pre[4][2][2];
; #pragma unroll
;             for (int m = m0; m < m0 + 2; ++m)
; #pragma unroll
;                 for (int bj = 0; bj < 2; ++bj) { const f32x4* p = (const f32x4*)(x + (size_t)(rowb + ai * 128 + m * 16) * 1024 + colb + bj * 128); pre[m][bj][0] = p[0]; pre[m][bj][1] = p[1]; }
; #pragma unroll
;             for (int m = m0; m < m0 + 2; ++m)
; #pragma unroll
;                 for (int bj = 0; bj < 2; ++bj) { f32x4* p = (f32x4*)(x + (size_t)(rowb + ai * 128 + m * 16) * 1024 + colb + bj * 128); p[0] = pre[m][bj][0] + acc[ai][bj][m][0]; p[1] = pre[m][bj][1] + acc[ai][bj][m][1]; }
;         }
;     }
	v_pk_add_f32 v[90:91], v[90:91], v[188:189]
	v_pk_add_f32 v[92:93], v[92:93], v[190:191]
	global_store_dwordx4 v[140:141], v[90:93], off offset:16
	v_pk_add_f32 v[94:95], v[94:95], v[192:193]
	v_pk_add_f32 v[96:97], v[96:97], v[194:195]
	global_store_dwordx4 v[140:141], v[94:97], off
	v_pk_add_f32 v[74:75], v[74:75], v[204:205]
	v_pk_add_f32 v[76:77], v[76:77], v[206:207]
	global_store_dwordx4 v[140:141], v[74:77], off offset:528
	v_pk_add_f32 v[78:79], v[78:79], v[208:209]
	v_pk_add_f32 v[80:81], v[80:81], v[210:211]
	global_store_dwordx4 v[140:141], v[78:81], off offset:512
	v_pk_add_f32 v[82:83], v[82:83], v[212:213]
	v_pk_add_f32 v[84:85], v[84:85], v[214:215]
	global_store_dwordx4 v[144:145], v[82:85], off offset:16
	v_pk_add_f32 v[86:87], v[86:87], v[216:217]
	v_pk_add_f32 v[88:89], v[88:89], v[218:219]
	global_store_dwordx4 v[144:145], v[86:89], off
	v_pk_add_f32 v[66:67], v[66:67], v[220:221]
	v_pk_add_f32 v[68:69], v[68:69], v[222:223]
	global_store_dwordx4 v[144:145], v[66:69], off offset:528
	v_pk_add_f32 v[70:71], v[70:71], v[224:225]
	v_pk_add_f32 v[72:73], v[72:73], v[226:227]
	global_store_dwordx4 v[144:145], v[70:73], off offset:512
	s_mov_b64 s[20:21], 0xa0000
	v_lshl_add_u64 v[140:141], v[184:185], 0, s[20:21]
	s_mov_b64 s[20:21], 0xb0000
	v_lshl_add_u64 v[144:145], v[184:185], 0, s[20:21]
	global_load_dwordx4 v[188:191], v[140:141], off offset:16
	global_load_dwordx4 v[192:195], v[140:141], off
	global_load_dwordx4 v[204:207], v[140:141], off offset:528
	global_load_dwordx4 v[208:211], v[140:141], off offset:512
	global_load_dwordx4 v[212:215], v[144:145], off offset:16
	global_load_dwordx4 v[216:219], v[144:145], off
	global_load_dwordx4 v[220:223], v[144:145], off offset:528
	global_load_dwordx4 v[224:227], v[144:145], off offset:512
	s_waitcnt vmcnt(16)
	v_pk_add_f32 v[58:59], v[58:59], v[152:153]
	v_pk_add_f32 v[60:61], v[60:61], v[154:155]
	global_store_dwordx4 v[186:187], v[58:61], off offset:16
	v_pk_add_f32 v[62:63], v[62:63], v[156:157]
	v_pk_add_f32 v[64:65], v[64:65], v[158:159]
	global_store_dwordx4 v[186:187], v[62:65], off
	v_pk_add_f32 v[42:43], v[42:43], v[160:161]
	v_pk_add_f32 v[44:45], v[44:45], v[162:163]
	global_store_dwordx4 v[186:187], v[42:45], off offset:528
	v_pk_add_f32 v[46:47], v[46:47], v[164:165]
	v_pk_add_f32 v[48:49], v[48:49], v[166:167]
	global_store_dwordx4 v[186:187], v[46:49], off offset:512
	v_pk_add_f32 v[50:51], v[50:51], v[168:169]
	v_pk_add_f32 v[52:53], v[52:53], v[170:171]
	global_store_dwordx4 v[146:147], v[50:53], off offset:16
	v_pk_add_f32 v[54:55], v[54:55], v[172:173]
	v_pk_add_f32 v[56:57], v[56:57], v[174:175]
	global_store_dwordx4 v[146:147], v[54:57], off
	v_pk_add_f32 v[34:35], v[34:35], v[176:177]
	v_pk_add_f32 v[36:37], v[36:37], v[178:179]
	global_store_dwordx4 v[146:147], v[34:37], off offset:528
	v_pk_add_f32 v[38:39], v[38:39], v[180:181]
	v_pk_add_f32 v[40:41], v[40:41], v[182:183]
	global_store_dwordx4 v[146:147], v[38:41], off offset:512
	s_waitcnt vmcnt(8)
	v_pk_add_f32 v[24:25], v[24:25], v[188:189]
	v_pk_add_f32 v[26:27], v[26:27], v[190:191]
	global_store_dwordx4 v[140:141], v[24:27], off offset:16
	v_pk_add_f32 v[28:29], v[28:29], v[192:193]
	v_pk_add_f32 v[30:31], v[30:31], v[194:195]
	global_store_dwordx4 v[140:141], v[28:31], off
	v_pk_add_f32 v[8:9], v[8:9], v[204:205]
	v_pk_add_f32 v[10:11], v[10:11], v[206:207]
	global_store_dwordx4 v[140:141], v[8:11], off offset:528
	v_pk_add_f32 v[16:17], v[16:17], v[208:209]
	v_pk_add_f32 v[18:19], v[18:19], v[210:211]
	global_store_dwordx4 v[140:141], v[16:19], off offset:512
	v_pk_add_f32 v[12:13], v[12:13], v[212:213]
	v_pk_add_f32 v[14:15], v[14:15], v[214:215]
	global_store_dwordx4 v[144:145], v[12:15], off offset:16
	v_pk_add_f32 v[20:21], v[20:21], v[216:217]
	v_pk_add_f32 v[22:23], v[22:23], v[218:219]
	global_store_dwordx4 v[144:145], v[20:23], off
	v_pk_add_f32 v[0:1], v[0:1], v[220:221]
	v_pk_add_f32 v[2:3], v[2:3], v[222:223]
	global_store_dwordx4 v[144:145], v[0:3], off offset:528
	v_pk_add_f32 v[4:5], v[4:5], v[224:225]
	v_pk_add_f32 v[6:7], v[6:7], v[226:227]
	global_store_dwordx4 v[144:145], v[4:7], off offset:512
	s_mov_b64 s[20:21], -1
	s_andn2_b64 vcc, exec, s[4:5]
	s_cbranch_vccnz .LBB0_212
	s_andn2_b64 vcc, exec, s[16:17]
	s_cbranch_vccnz .LBB0_211
	s_barrier
	s_branch .LBB0_211
